# LRU carry segments: fwd packs (h, gate) with one cvt, bwd converts two outputs per cvt + d16_hi LDS store (on top of priority scheme)
# speedup vs baseline: 1.0072x; 1.0072x over previous
; #define LAS __attribute__((address_space(3)))
; __device__ __forceinline__ unsigned cvt_pk_bf16(float lo, float hi) { unsigned r; asm volatile("v_cvt_pk_bf16_f32 %0, %1, %2" : "=v"(r) : "v"(lo), "v"(hi)); return r; }
; __device__ __forceinline__ float bf_lo(unsigned u) { return __uint_as_float(u << 16); }
; __device__ __forceinline__ float bf_hi(unsigned u) { return __uint_as_float(u & 0xffff0000u); }
; __device__ __forceinline__ bf16_t f2bf(float f) { return (bf16_t)(cvt_pk_bf16(f, 0.f) & 0xffffu); }
; #define LDS_BARRIER() do { asm volatile("s_waitcnt lgkmcnt(0)" ::: "memory"); __builtin_amdgcn_s_barrier(); asm volatile("" ::: "memory"); } while (0)
; template <int dir>
; __device__ __forceinline__ void lru_pass(LAS unsigned char* lds, const Params& P, int b, int h, int q, bool dry) {
;     ...
;             LDS_BARRIER();
;             float cin = carry, cend = carry;
; #pragma unroll
;             for (int w = 0; w < 8; ++w) { const float pw = AGG[(w * 2 + 0) * 32 + nl], ew = AGG[(w * 2 + 1) * 32 + nl]; if (w == wid) cin = cend; cend = fmaf(pw, cend, ew); }
;             carry = cend;
;             if (g) cin = fmaf(P0, cin, E0);
;             if (!isctx) {
; #pragma unroll
;                 for (int v = 0; v < 16; ++v) { const float hv = fmaf(zi[v], cin, zr[v]);
;                     const int s = sbase + v; const int tl = dir == 0 ? s : 255 - s;
;                     if (dir == 0) *(LAS unsigned*)(TOUT + tl * IO_WP + nl * 4) = (cvt_pk_bf16(hv, 0.f) & 0xffffu) | (pk[v] << 16);
;                     else *(LAS bf16_t*)(TOUT + tl * IO_NP + nl * 2) = f2bf((bf_lo(pk[v]) + hv) * bf_hi(pk[v])); }
.LBB0_299:
	s_or_b64 exec, exec, s[18:19]
	s_waitcnt lgkmcnt(0)
	s_barrier
	s_setprio 1
	v_add_u32_e32 v34, s99, v140
	ds_read2_b32 v[36:37], v34 offset1:32
	ds_read2_b32 v[38:39], v34 offset0:64 offset1:96
	ds_read2_b32 v[40:41], v34 offset0:128 offset1:160
	ds_read2_b32 v[42:43], v34 offset0:192 offset1:224
	v_add_u32_e32 v32, s100, v140
	ds_read2_b32 v[44:45], v32 offset1:32
	s_waitcnt lgkmcnt(4)
	v_fmac_f32_e32 v37, v36, v165
	ds_read2_b32 v[46:47], v32 offset0:64 offset1:96
	s_waitcnt lgkmcnt(4)
	v_fmac_f32_e32 v39, v38, v37
	ds_read2_b32 v[34:35], v32 offset0:128 offset1:160
	s_waitcnt lgkmcnt(4)
	v_fmac_f32_e32 v41, v40, v39
	ds_read2_b32 v[32:33], v32 offset0:192 offset1:224
	s_waitcnt lgkmcnt(4)
	v_fmac_f32_e32 v43, v42, v41
	s_waitcnt lgkmcnt(3)
	v_fmac_f32_e32 v45, v44, v43
	s_waitcnt lgkmcnt(2)
	v_fmac_f32_e32 v47, v46, v45
	s_cmp_eq_u32 s80, 0
	s_waitcnt lgkmcnt(1)
	v_fmac_f32_e32 v35, v34, v47
	s_cbranch_scc1 .LBB0_301
	v_cndmask_b32_e64 v37, v165, v37, s[14:15]
	v_cndmask_b32_e64 v37, v37, v39, s[12:13]
	v_cndmask_b32_e64 v37, v37, v41, s[10:11]
	v_cndmask_b32_e64 v37, v37, v43, s[8:9]
	v_cndmask_b32_e64 v37, v37, v45, s[4:5]
	v_cndmask_b32_e64 v37, v37, v47, s[16:17]
	v_cndmask_b32_e32 v34, v188, v187, vcc
	v_cndmask_b32_e32 v36, v189, v185, vcc
	v_cndmask_b32_e64 v37, v37, v35, s[0:1]
	v_fmac_f32_e32 v36, v34, v37
	v_cndmask_b32_e32 v34, v36, v37, vcc
	v_fmac_f32_e32 v49, v171, v34
	v_fmac_f32_e32 v172, v50, v34
	v_fmac_f32_e32 v173, v51, v34
	v_fmac_f32_e32 v174, v52, v34
	v_fmac_f32_e32 v175, v53, v34
	v_fmac_f32_e32 v176, v54, v34
	v_fmac_f32_e32 v177, v55, v34
	v_fmac_f32_e32 v178, v56, v34
	v_fmac_f32_e32 v179, v57, v34
	v_fmac_f32_e32 v180, v58, v34
	v_fmac_f32_e32 v181, v59, v34
	v_fmac_f32_e32 v182, v60, v34
	v_fmac_f32_e32 v183, v61, v34
	v_fmac_f32_e32 v184, v62, v34
	v_fmac_f32_e32 v63, v186, v34
	v_fmac_f32_e32 v185, v187, v34
	v_lshlrev_b32_e32 v37, 16, v127
	v_cvt_pk_bf16_f32 v36, v49, v37
	ds_write_b32 v164, v36
	v_lshlrev_b32_e32 v39, 16, v124
	v_cvt_pk_bf16_f32 v38, v172, v39
	ds_write_b32 v164, v38 offset:144
	v_lshlrev_b32_e32 v41, 16, v121
	v_cvt_pk_bf16_f32 v40, v173, v41
	ds_write_b32 v164, v40 offset:288
	v_lshlrev_b32_e32 v43, 16, v66
	v_cvt_pk_bf16_f32 v42, v174, v43
	ds_write_b32 v164, v42 offset:432
	v_lshlrev_b32_e32 v37, 16, v64
	v_cvt_pk_bf16_f32 v36, v175, v37
	ds_write_b32 v164, v36 offset:576
	v_lshlrev_b32_e32 v39, 16, v126
	v_cvt_pk_bf16_f32 v38, v176, v39
	ds_write_b32 v164, v38 offset:720
	v_lshlrev_b32_e32 v41, 16, v123
	v_cvt_pk_bf16_f32 v40, v177, v41
	ds_write_b32 v164, v40 offset:864
	v_lshlrev_b32_e32 v43, 16, v120
	v_cvt_pk_bf16_f32 v42, v178, v43
	ds_write_b32 v164, v42 offset:1008
	v_lshlrev_b32_e32 v37, 16, v170
	v_cvt_pk_bf16_f32 v36, v179, v37
	ds_write_b32 v164, v36 offset:1152
	v_lshlrev_b32_e32 v39, 16, v169
	v_cvt_pk_bf16_f32 v38, v180, v39
	ds_write_b32 v164, v38 offset:1296
	v_lshlrev_b32_e32 v41, 16, v168
	v_cvt_pk_bf16_f32 v40, v181, v41
	ds_write_b32 v164, v40 offset:1440
	v_lshlrev_b32_e32 v43, 16, v166
	v_cvt_pk_bf16_f32 v42, v182, v43
	ds_write_b32 v164, v42 offset:1584
	v_lshlrev_b32_e32 v37, 16, v125
	v_cvt_pk_bf16_f32 v36, v183, v37
	ds_write_b32 v164, v36 offset:1728
	v_lshlrev_b32_e32 v39, 16, v122
	v_cvt_pk_bf16_f32 v38, v184, v39
	ds_write_b32 v164, v38 offset:1872
	v_lshlrev_b32_e32 v41, 16, v67
	v_cvt_pk_bf16_f32 v40, v63, v41
	ds_write_b32 v164, v40 offset:2016
	v_lshlrev_b32_e32 v43, 16, v48
	v_cvt_pk_bf16_f32 v42, v185, v43
	ds_write_b32 v164, v42 offset:2160

; #define LAS __attribute__((address_space(3)))
; __device__ __forceinline__ unsigned cvt_pk_bf16(float lo, float hi) { unsigned r; asm volatile("v_cvt_pk_bf16_f32 %0, %1, %2" : "=v"(r) : "v"(lo), "v"(hi)); return r; }
; __device__ __forceinline__ float bf_lo(unsigned u) { return __uint_as_float(u << 16); }
; __device__ __forceinline__ float bf_hi(unsigned u) { return __uint_as_float(u & 0xffff0000u); }
; __device__ __forceinline__ bf16_t f2bf(float f) { return (bf16_t)(cvt_pk_bf16(f, 0.f) & 0xffffu); }
; #define LDS_BARRIER() do { asm volatile("s_waitcnt lgkmcnt(0)" ::: "memory"); __builtin_amdgcn_s_barrier(); asm volatile("" ::: "memory"); } while (0)
; template <int dir>
; __device__ __forceinline__ void lru_pass(LAS unsigned char* lds, const Params& P, int b, int h, int q, bool dry) {
;     ...
;             LDS_BARRIER();
;             float cin = carry, cend = carry;
; #pragma unroll
;             for (int w = 0; w < 8; ++w) { const float pw = AGG[(w * 2 + 0) * 32 + nl], ew = AGG[(w * 2 + 1) * 32 + nl]; if (w == wid) cin = cend; cend = fmaf(pw, cend, ew); }
;             carry = cend;
;             if (g) cin = fmaf(P0, cin, E0);
;             if (!isctx) {
; #pragma unroll
;                 for (int v = 0; v < 16; ++v) { const float hv = fmaf(zi[v], cin, zr[v]);
;                     const int s = sbase + v; const int tl = dir == 0 ? s : 255 - s;
;                     if (dir == 0) *(LAS unsigned*)(TOUT + tl * IO_WP + nl * 4) = (cvt_pk_bf16(hv, 0.f) & 0xffffu) | (pk[v] << 16);
;                     else *(LAS bf16_t*)(TOUT + tl * IO_NP + nl * 2) = f2bf((bf_lo(pk[v]) + hv) * bf_hi(pk[v])); }
.LBB0_313:
	s_or_b64 exec, exec, s[18:19]
	s_waitcnt lgkmcnt(0)
	s_barrier
	s_setprio 1
	v_add_u32_e32 v34, s99, v161
	ds_read2_b32 v[36:37], v34 offset1:32
	ds_read2_b32 v[38:39], v34 offset0:64 offset1:96
	ds_read2_b32 v[40:41], v34 offset0:128 offset1:160
	ds_read2_b32 v[42:43], v34 offset0:192 offset1:224
	v_add_u32_e32 v32, s100, v161
	s_waitcnt lgkmcnt(3)
	v_fmac_f32_e32 v37, v36, v222
	s_waitcnt lgkmcnt(2)
	v_fmac_f32_e32 v39, v38, v37
	s_waitcnt lgkmcnt(1)
	v_fmac_f32_e32 v41, v40, v39
	ds_read2_b32 v[44:45], v32 offset1:32
	ds_read2_b32 v[46:47], v32 offset0:64 offset1:96
	ds_read2_b32 v[34:35], v32 offset0:128 offset1:160
	ds_read2_b32 v[32:33], v32 offset0:192 offset1:224
	s_waitcnt lgkmcnt(4)
	v_fmac_f32_e32 v43, v42, v41
	s_waitcnt lgkmcnt(3)
	v_fmac_f32_e32 v45, v44, v43
	s_waitcnt lgkmcnt(2)
	v_fmac_f32_e32 v47, v46, v45
	s_cmp_eq_u32 s44, 0
	s_waitcnt lgkmcnt(1)
	v_fmac_f32_e32 v35, v34, v47
	s_cbranch_scc1 .LBB0_315
	v_cndmask_b32_e64 v37, v222, v37, s[14:15]
	v_cndmask_b32_e64 v37, v37, v39, s[12:13]
	v_cndmask_b32_e64 v37, v37, v41, s[10:11]
	v_cndmask_b32_e64 v37, v37, v43, s[8:9]
	v_cndmask_b32_e64 v37, v37, v45, s[4:5]
	v_cndmask_b32_e64 v37, v37, v47, s[16:17]
	v_cndmask_b32_e32 v34, v244, v242, vcc
	v_cndmask_b32_e32 v36, v245, v241, vcc
	v_cndmask_b32_e64 v37, v37, v35, s[0:1]
	v_fmac_f32_e32 v36, v34, v37
	v_cndmask_b32_e32 v34, v36, v37, vcc
	v_fmac_f32_e32 v49, v227, v34
	v_fmac_f32_e32 v228, v50, v34
	v_fmac_f32_e32 v229, v51, v34
	v_fmac_f32_e32 v230, v52, v34
	v_fmac_f32_e32 v231, v53, v34
	v_fmac_f32_e32 v232, v54, v34
	v_fmac_f32_e32 v233, v55, v34
	v_fmac_f32_e32 v234, v56, v34
	v_fmac_f32_e32 v235, v57, v34
	v_fmac_f32_e32 v236, v58, v34
	v_fmac_f32_e32 v237, v59, v34
	v_fmac_f32_e32 v238, v60, v34
	v_fmac_f32_e32 v239, v61, v34
	v_fmac_f32_e32 v240, v62, v34
	v_fmac_f32_e32 v63, v243, v34
	v_fmac_f32_e32 v241, v242, v34
	v_lshlrev_b32_e32 v36, 16, v226
	v_lshlrev_b32_e32 v38, 16, v225
	v_add_f32_e32 v36, v49, v36
	v_add_f32_e32 v38, v228, v38
	v_and_b32_e32 v37, 0xffff0000, v226
	v_and_b32_e32 v39, 0xffff0000, v225
	v_mul_f32_e32 v36, v36, v37
	v_mul_f32_e32 v38, v38, v39
	v_cvt_pk_bf16_f32 v36, v36, v38
	ds_write_b16 v206, v36
	ds_write_b16_d16_hi v207, v36
	v_lshlrev_b32_e32 v40, 16, v224
	v_lshlrev_b32_e32 v42, 16, v223
	v_add_f32_e32 v40, v229, v40
	v_add_f32_e32 v42, v230, v42
	v_and_b32_e32 v41, 0xffff0000, v224
	v_and_b32_e32 v43, 0xffff0000, v223
	v_mul_f32_e32 v40, v40, v41
	v_mul_f32_e32 v42, v42, v43
	v_cvt_pk_bf16_f32 v40, v40, v42
	ds_write_b16 v208, v40
	ds_write_b16_d16_hi v209, v40
	v_lshlrev_b32_e32 v36, 16, v135
	v_lshlrev_b32_e32 v38, 16, v134
	v_add_f32_e32 v36, v231, v36
	v_add_f32_e32 v38, v232, v38
	v_and_b32_e32 v37, 0xffff0000, v135
	v_and_b32_e32 v39, 0xffff0000, v134
	v_mul_f32_e32 v36, v36, v37
	v_mul_f32_e32 v38, v38, v39
	v_cvt_pk_bf16_f32 v36, v36, v38
	ds_write_b16 v210, v36
	ds_write_b16_d16_hi v211, v36
	v_lshlrev_b32_e32 v40, 16, v133
	v_lshlrev_b32_e32 v42, 16, v131
	v_add_f32_e32 v40, v233, v40
	v_add_f32_e32 v42, v234, v42
	v_and_b32_e32 v41, 0xffff0000, v133
	v_and_b32_e32 v43, 0xffff0000, v131
	v_mul_f32_e32 v40, v40, v41
	v_mul_f32_e32 v42, v42, v43
	v_cvt_pk_bf16_f32 v40, v40, v42
	ds_write_b16 v212, v40
	ds_write_b16_d16_hi v213, v40
	v_lshlrev_b32_e32 v36, 16, v132
	v_lshlrev_b32_e32 v38, 16, v130
	v_add_f32_e32 v36, v235, v36
	v_add_f32_e32 v38, v236, v38
	v_and_b32_e32 v37, 0xffff0000, v132
	v_and_b32_e32 v39, 0xffff0000, v130
	v_mul_f32_e32 v36, v36, v37
	v_mul_f32_e32 v38, v38, v39
	v_cvt_pk_bf16_f32 v36, v36, v38
	ds_write_b16 v214, v36
	ds_write_b16_d16_hi v215, v36
	v_lshlrev_b32_e32 v40, 16, v129
	v_lshlrev_b32_e32 v42, 16, v128
	v_add_f32_e32 v40, v237, v40
	v_add_f32_e32 v42, v238, v42
	v_and_b32_e32 v41, 0xffff0000, v129
	v_and_b32_e32 v43, 0xffff0000, v128
	v_mul_f32_e32 v40, v40, v41
	v_mul_f32_e32 v42, v42, v43
	v_cvt_pk_bf16_f32 v40, v40, v42
	ds_write_b16 v216, v40
	ds_write_b16_d16_hi v217, v40
	v_lshlrev_b32_e32 v36, 16, v67
	v_lshlrev_b32_e32 v38, 16, v66
	v_add_f32_e32 v36, v239, v36
	v_add_f32_e32 v38, v240, v38
	v_and_b32_e32 v37, 0xffff0000, v67
	v_and_b32_e32 v39, 0xffff0000, v66
	v_mul_f32_e32 v36, v36, v37
	v_mul_f32_e32 v38, v38, v39
	v_cvt_pk_bf16_f32 v36, v36, v38
	ds_write_b16 v218, v36
	ds_write_b16_d16_hi v219, v36
	v_lshlrev_b32_e32 v40, 16, v64
	v_lshlrev_b32_e32 v42, 16, v48
	v_add_f32_e32 v40, v63, v40
	v_add_f32_e32 v42, v241, v42
	v_and_b32_e32 v41, 0xffff0000, v64
	v_and_b32_e32 v43, 0xffff0000, v48
	v_mul_f32_e32 v40, v40, v41
	v_mul_f32_e32 v42, v42, v43
	v_cvt_pk_bf16_f32 v40, v40, v42
	ds_write_b16 v220, v40
	ds_write_b16_d16_hi v221, v40
